# skip the grid barrier after the last layer's FFN2 (kernel end is the barrier)
# speedup vs baseline: 1.0064x; 1.0009x over previous
; __device__ __forceinline__ void grid_barrier(int wid_s, unsigned* bar, volatile unsigned* st) { int nb = 1 + RB(8); asm volatile("" : "+s"(nb)); for (int q = 0; q < nb; ++q) grid_barrier1(wid_s, bar, st); }
; __device__ __forceinline__ unsigned char* wsl_(KP p) { unsigned char* w = p->ws; asm volatile("" : "+s"(w)); return w; }
; __global__ void __launch_bounds__(512, 2) fwd_kernel(Params parg) {
;     ...
;         { int nw = 1 + RB(18); asm volatile("" : "+s"(nw)); for (int q = 0; q < nw; ++q) { EpiRes E{l == 1 ? xcur : nullptr, xb, part, q + 1 < nw}; run_gemm(wid_s, lds3, (const bf16*)(wsl_(p) + R_H), DFF, (const bf16*)(wsl_(p) + W_2), T, 1024, DFF, E); if (q + 1 < nw) grid_barrier(wid_s, ctl + 1024, bst); } }
;         grid_barrier(wid_s, ctl + 1024, bst);
.LBB0_3101:
	v_readlane_b32 s0, v255, 12
	s_cmp_eq_u32 s0, 0
	s_cselect_b32 s0, 1, 0
	s_cmp_lt_i32 s0, 1
	s_cbranch_scc0 .LBB0_3102
	s_getpc_b64 s[98:99]
